# P1 idle-workgroup weight transposes hand-written with next-item load prefetch (two register sets)
# baseline (speedup 1.0000x reference)
; #define SEAM(k) do { if (IN(k) && IN((k) + 1)) xcd_barrier(xbar); } while (0)
; __device__ __forceinline__ void prep_transposes(const Params& p, LAS unsigned char* lds, int lo, int hi, int widx, int wcnt) {
;     ...
;     for (int it = lo + widx; it < hi; it += wcnt) {
;         int r = it;
;         if (r < I_WIN) { const int kb = r / 53, nb = r % 53; transpose_item(p.in[3], INC, p.in[2], (bf16_t*)(ws + WS_WIN), 1024, 32 * nb, 64 * kb, 32 * nb, scr, lane); continue; } r -= I_WIN;
;         if (r < I_UQ) { const int kb = r / 24, nb = r % 24; transpose_item(p.in[5], 768, p.in[4], (bf16_t*)(ws + WS_WUQ), 384, 32 * nb, 64 * kb, 32 * nb, scr, lane); continue; } r -= I_UQ;
;         if (r < I_UKV) { const int kb = r / 32, nb = r % 32; transpose_item(p.in[7], 1024, p.in[6], (bf16_t*)(ws + WS_WUKV), 256, 32 * nb, 64 * kb, 32 * nb, scr, lane); continue; } r -= I_UKV;
;         if (r < I_OUT) { const int kb = r / 32, nb = r % 32; const float* gn = (kb < 8) ? p.in[17] : (p.in[18] - 512); transpose_item(p.in[19], 1024, gn, (bf16_t*)(ws + WS_WOUT), 1024, 32 * nb, 64 * kb, 32 * nb, scr, lane); continue; } r -= I_OUT;
;         if (r < 2 * I_G) { const int up = r >= I_G; if (up) r -= I_G; const int kb = r / 88, nb = r % 88; const int n0 = 32 * nb; const int drow = 256 * (n0 >> 7) + (n0 & 127) + (up ? 128 : 0);
;             transpose_item(up ? p.in[22] : p.in[21], DFF, p.in[20], (bf16_t*)(ws + WS_WGU), 1024, drow, 64 * kb, n0, scr, lane); continue; } r -= 2 * I_G;
;         { const int kb = r / 32, nb = r % 32; transpose_item(p.in[23], 1024, nullptr, (bf16_t*)(ws + WS_WDN), DFF, 32 * nb, 64 * kb, 32 * nb, scr, lane); }
; __global__ void __launch_bounds__(512, 2) hymba_fwd(Params p) {
;     ...
;           const int nwg = (MT / 256) * (INP / 256), rounds = (nwg + G - 1) / G, first_idle = nwg - (rounds - 1) * G;
;           const int n_idle = G - first_idle;
;           if (n_idle <= 0) prep_transposes(p, lds, I_WIN, NIT, bx * 8 + (int)(threadIdx.x >> 6), G * 8);
;           else if (bx >= first_idle) prep_transposes(p, lds, I_WIN, NIT, (bx - first_idle) * 8 + (int)(threadIdx.x >> 6), n_idle * 8); } } SEAM(1);
.LBB0_221:
	s_abs_i32 s0, s28
	v_cvt_f32_u32_e32 v0, s0
	s_sub_i32 s3, 0, s0
	s_add_i32 s1, s28, 0x386
	s_xor_b32 s2, s1, s28
	v_rcp_iflag_f32_e32 v0, v0
	s_abs_i32 s1, s1
	s_ashr_i32 s2, s2, 31
	v_mul_f32_e32 v0, 0x4f7ffffe, v0
	v_cvt_u32_f32_e32 v0, v0
	s_nop 0
	v_readfirstlane_b32 s4, v0
	s_mul_i32 s3, s3, s4
	s_mul_hi_u32 s3, s4, s3
	s_add_i32 s4, s4, s3
	s_mul_hi_u32 s3, s1, s4
	s_mul_i32 s4, s3, s0
	s_sub_i32 s1, s1, s4
	s_add_i32 s5, s3, 1
	s_sub_i32 s4, s1, s0
	s_cmp_ge_u32 s1, s0
	s_cselect_b32 s3, s5, s3
	s_cselect_b32 s1, s4, s1
	s_add_i32 s4, s3, 1
	s_cmp_ge_u32 s1, s0
	s_cselect_b32 s0, s4, s3
	s_xor_b32 s3, s0, s2
	s_sub_i32 s11, s3, s2
	s_add_i32 s34, s11, -1
	s_mul_i32 s34, s34, s28
	s_sub_i32 s4, 0x387, s34
	s_sub_i32 s6, s28, s4
	s_cmp_gt_i32 s6, 0
	s_mov_b64 s[0:1], -1
	s_cbranch_scc0 .LBB0_319
	s_cmp_lt_i32 s18, s4
	s_cbranch_scc1 .LBB0_318
	s_sub_i32 s0, s18, s4
	v_lshl_add_u32 v0, s0, 3, v162
	s_movk_i32 s0, 0x1390
	v_cmp_gt_u32_e32 vcc, s0, v0
	s_and_saveexec_b64 s[4:5], vcc
	s_cbranch_execz .LBB0_317
	v_readfirstlane_b32 s33, v0
	v_readfirstlane_b32 s1, v162
	v_and_b32_e32 v0, 63, v163
	v_lshrrev_b32_e32 v1, 3, v0
	v_and_b32_e32 v2, 7, v0
	s_addk_i32 s33, 0x350
	s_lshl_b32 s34, s6, 3
	s_lshl_b32 s35, s1, 14
	v_mul_u32_u24_e32 v3, 33, v1
	v_lshl_add_u32 v3, v2, 2, v3
	v_lshl_add_u32 v3, v3, 2, s35
	v_mul_u32_u24_e32 v4, 0x108, v2
	v_add_u32_e32 v4, v4, v1
	v_lshl_add_u32 v4, v4, 2, s35
	v_lshlrev_b32_e32 v5, 2, v1
	v_lshlrev_b32_e32 v6, 4, v2
	v_readlane_b32 s52, v244, 21
	v_readlane_b32 s53, v244, 22
	v_readlane_b32 s54, v244, 23
	v_readlane_b32 s55, v244, 24
	v_readlane_b32 s56, v244, 25
	v_readlane_b32 s57, v244, 26
	v_readlane_b32 s58, v244, 27
	v_readlane_b32 s59, v244, 28
	v_readlane_b32 s60, v244, 29
	v_readlane_b32 s61, v244, 30
	v_readlane_b32 s62, v244, 31
	v_readlane_b32 s63, v244, 32
	v_readlane_b32 s64, v244, 33
	v_readlane_b32 s65, v244, 34
	s_cmpk_ge_u32 s33, 0x16e0
	s_cbranch_scc1 .Lxp_done
	s_sub_i32 s0, s33, 0x350
	s_cmp_lt_u32 s0, 0x90
	s_cbranch_scc0 .Lxp_a0_c1
	s_mul_i32 s30, s0, 171
	s_lshr_b32 s30, s30, 12
	s_mul_i32 s1, s30, 24
	s_sub_i32 s31, s0, s1
	s_mov_b64 s[8:9], s[46:47]
	s_movk_i32 s10, 0x300
	s_mov_b64 s[14:15], s[44:45]
	s_mov_b32 s16, 0
	s_mov_b32 s17, 0x900000
	s_movk_i32 s19, 0x180
	s_lshl_b32 s38, s31, 5
	s_branch .Lxp_a0_dec
.Lxp_a0_c1:
	s_sub_i32 s0, s0, 0x90
	s_cmp_lt_u32 s0, 0x80
	s_cbranch_scc0 .Lxp_a0_c2
	s_lshr_b32 s30, s0, 5
	s_and_b32 s31, s0, 31
	s_mov_b64 s[8:9], s[50:51]
	s_movk_i32 s10, 0x400
	s_mov_b64 s[14:15], s[48:49]
	s_mov_b32 s16, 0
	s_mov_b32 s17, 0xa00000
	s_movk_i32 s19, 0x100
	s_lshl_b32 s38, s31, 5
	s_branch .Lxp_a0_dec
.Lxp_a0_c2:
	s_sub_i32 s0, s0, 0x80
	s_cmp_lt_u32 s0, 0x200
	s_cbranch_scc0 .Lxp_a0_c3
	s_lshr_b32 s30, s0, 5
	s_and_b32 s31, s0, 31
	s_mov_b64 s[8:9], s[56:57]
	s_movk_i32 s10, 0x400
	s_add_u32 s14, s54, 0xfffff800
	s_addc_u32 s15, s55, -1
	s_cmp_lt_u32 s30, 8
	s_cselect_b32 s14, s52, s14
	s_cselect_b32 s15, s53, s15
	s_mov_b32 s16, 0
	s_mov_b32 s17, 0xb00000
	s_movk_i32 s19, 0x400
	s_lshl_b32 s38, s31, 5
	s_branch .Lxp_a0_dec
.Lxp_a0_c3:
	s_sub_i32 s0, s0, 0x200
	s_cmp_lt_u32 s0, 0xb00
	s_cbranch_scc0 .Lxp_a0_c4
	s_cmp_ge_u32 s0, 0x580
	s_cselect_b32 s1, 0x580, 0
	s_cselect_b32 s2, 0x80, 0
	s_cselect_b32 s8, s62, s60
	s_cselect_b32 s9, s63, s61
	s_sub_i32 s0, s0, s1
	s_mul_i32 s30, s0, 745
	s_lshr_b32 s30, s30, 16
	s_mul_i32 s1, s30, 88
	s_sub_i32 s31, s0, s1
	s_movk_i32 s10, 0xb00
	s_mov_b64 s[14:15], s[58:59]
	s_mov_b32 s16, 0
	s_mov_b32 s17, 0xd00000
	s_movk_i32 s19, 0x400
	s_lshl_b32 s3, s31, 5
	s_lshr_b32 s38, s3, 7
	s_lshl_b32 s38, s38, 8
	s_and_b32 s3, s3, 0x7f
	s_add_i32 s38, s38, s3
	s_add_i32 s38, s38, s2
	s_branch .Lxp_a0_dec
.Lxp_a0_c4:
	s_sub_i32 s0, s0, 0xb00
	s_lshr_b32 s30, s0, 5
	s_and_b32 s31, s0, 31
	s_mov_b64 s[8:9], s[64:65]
	s_movk_i32 s10, 0x400
	s_mov_b64 s[14:15], s[64:65]
	s_mov_b32 s16, 1
	s_mov_b32 s17, 0x1900000
	s_movk_i32 s19, 0xb00
	s_lshl_b32 s38, s31, 5
.Lxp_a0_dec:
	s_lshl_b32 s30, s30, 6
	s_lshl_b32 s39, s31, 5
	s_mul_i32 s0, s30, s10
	s_add_i32 s0, s0, s39
	s_lshl_b32 s0, s0, 2
	s_add_u32 s8, s8, s0
	s_addc_u32 s9, s9, 0
	s_lshl_b32 s0, s30, 2
	s_add_u32 s14, s14, s0
	s_addc_u32 s15, s15, 0
	s_mul_i32 s0, s38, s19
	s_add_i32 s0, s0, s30
	s_lshl_b32 s0, s0, 1
	s_add_u32 s0, s0, s17
	s_add_u32 s66, s22, s0
	s_addc_u32 s67, s23, 0
	s_lshl_b32 s68, s19, 4
	s_lshl_b32 s0, s19, 1
	v_mad_u32_u24 v48, v1, s0, v6
	s_lshl_b32 s0, s10, 2
	v_mad_u32_u24 v7, v1, s0, v6
	s_lshl_b32 s0, s0, 3
	global_load_dwordx4 v[8:11], v7, s[8:9]
	s_add_u32 s8, s8, s0
	s_addc_u32 s9, s9, 0
	global_load_dwordx4 v[12:15], v7, s[8:9]
	s_add_u32 s8, s8, s0
	s_addc_u32 s9, s9, 0
	global_load_dwordx4 v[16:19], v7, s[8:9]
	s_add_u32 s8, s8, s0
	s_addc_u32 s9, s9, 0
	global_load_dwordx4 v[20:23], v7, s[8:9]
	s_add_u32 s8, s8, s0
	s_addc_u32 s9, s9, 0
	global_load_dwordx4 v[24:27], v7, s[8:9]
	s_add_u32 s8, s8, s0
	s_addc_u32 s9, s9, 0
	global_load_dwordx4 v[28:31], v7, s[8:9]
	s_add_u32 s8, s8, s0
	s_addc_u32 s9, s9, 0
	global_load_dwordx4 v[32:35], v7, s[8:9]
	s_add_u32 s8, s8, s0
	s_addc_u32 s9, s9, 0
	global_load_dwordx4 v[36:39], v7, s[8:9]
	global_load_dword v40, v5, s[14:15]
	global_load_dword v41, v5, s[14:15] offset:32
	global_load_dword v42, v5, s[14:15] offset:64
	global_load_dword v43, v5, s[14:15] offset:96
	global_load_dword v44, v5, s[14:15] offset:128
	global_load_dword v45, v5, s[14:15] offset:160
	global_load_dword v46, v5, s[14:15] offset:192
	global_load_dword v47, v5, s[14:15] offset:224
	s_mov_b32 s69, s16
	s_add_i32 s33, s33, s34
	s_cmpk_lt_u32 s33, 0x16e0
	s_cbranch_scc0 .Lxp_lastA
	s_sub_i32 s0, s33, 0x350
	s_cmp_lt_u32 s0, 0x90
	s_cbranch_scc0 .Lxp_b0_c1
	s_mul_i32 s30, s0, 171
	s_lshr_b32 s30, s30, 12
	s_mul_i32 s1, s30, 24
	s_sub_i32 s31, s0, s1
	s_mov_b64 s[8:9], s[46:47]
	s_movk_i32 s10, 0x300
	s_mov_b64 s[14:15], s[44:45]
	s_mov_b32 s16, 0
	s_mov_b32 s17, 0x900000
	s_movk_i32 s19, 0x180
	s_lshl_b32 s38, s31, 5
	s_branch .Lxp_b0_dec

; #define LAS __attribute__((address_space(3)))
; __device__ __forceinline__ unsigned cvt_pk(float lo, float hi) { unsigned r; asm("v_cvt_pk_bf16_f32 %0, %1, %2" : "=v"(r) : "v"(lo), "v"(hi)); return r; }
; __device__ __forceinline__ void transpose_item(const float* W, int N, const float* gain, bf16_t* WT, int ldt, int dst_row0, int k0, int n0, LAS float* scr, int lane) {
;     { const int kq = lane >> 3, nq = lane & 7;
;       f32x4 v[8]; float gv[8];
; #pragma unroll
;       for (int i = 0; i < 8; ++i) { const int kk = 8 * i + kq; gv[i] = gain ? gain[k0 + kk] : 1.0f; v[i] = *(const f32x4*)(W + (size_t)(k0 + kk) * N + n0 + 4 * nq); }
; #pragma unroll
;       for (int i = 0; i < 8; ++i) { const int kk = 8 * i + kq; LAS float* d = scr + kk * 33 + 4 * nq; d[0] = v[i][0] * gv[i]; d[1] = v[i][1] * gv[i]; d[2] = v[i][2] * gv[i]; d[3] = v[i][3] * gv[i]; } }
;     asm volatile("s_waitcnt lgkmcnt(0)" ::: "memory");
;     const int c = lane & 7;
; #pragma unroll
;     for (int j = 0; j < 4; ++j) { const int n = (lane >> 3) + 8 * j; const LAS float* s = scr + (8 * c) * 33 + n;
;         u32x4 o; o.x = cvt_pk(s[0 * 33], s[1 * 33]); o.y = cvt_pk(s[2 * 33], s[3 * 33]); o.z = cvt_pk(s[4 * 33], s[5 * 33]); o.w = cvt_pk(s[6 * 33], s[7 * 33]);
;         *(u32x4*)(WT + (size_t)(dst_row0 + n) * ldt + k0 + 8 * c) = o; }
;     asm volatile("s_waitcnt lgkmcnt(0)" ::: "memory");
; }
.Lxp_b0_dec:
	s_lshl_b32 s30, s30, 6
	s_lshl_b32 s39, s31, 5
	s_mul_i32 s0, s30, s10
	s_add_i32 s0, s0, s39
	s_lshl_b32 s0, s0, 2
	s_add_u32 s8, s8, s0
	s_addc_u32 s9, s9, 0
	s_lshl_b32 s0, s30, 2
	s_add_u32 s14, s14, s0
	s_addc_u32 s15, s15, 0
	s_mul_i32 s0, s38, s19
	s_add_i32 s0, s0, s30
	s_lshl_b32 s0, s0, 1
	s_add_u32 s0, s0, s17
	s_add_u32 s70, s22, s0
	s_addc_u32 s71, s23, 0
	s_lshl_b32 s72, s19, 4
	s_lshl_b32 s0, s19, 1
	v_mad_u32_u24 v90, v1, s0, v6
	s_lshl_b32 s0, s10, 2
	v_mad_u32_u24 v7, v1, s0, v6
	s_lshl_b32 s0, s0, 3
	global_load_dwordx4 v[50:53], v7, s[8:9]
	s_add_u32 s8, s8, s0
	s_addc_u32 s9, s9, 0
	global_load_dwordx4 v[54:57], v7, s[8:9]
	s_add_u32 s8, s8, s0
	s_addc_u32 s9, s9, 0
	global_load_dwordx4 v[58:61], v7, s[8:9]
	s_add_u32 s8, s8, s0
	s_addc_u32 s9, s9, 0
	global_load_dwordx4 v[62:65], v7, s[8:9]
	s_add_u32 s8, s8, s0
	s_addc_u32 s9, s9, 0
	global_load_dwordx4 v[66:69], v7, s[8:9]
	s_add_u32 s8, s8, s0
	s_addc_u32 s9, s9, 0
	global_load_dwordx4 v[70:73], v7, s[8:9]
	s_add_u32 s8, s8, s0
	s_addc_u32 s9, s9, 0
	global_load_dwordx4 v[74:77], v7, s[8:9]
	s_add_u32 s8, s8, s0
	s_addc_u32 s9, s9, 0
	global_load_dwordx4 v[78:81], v7, s[8:9]
	global_load_dword v82, v5, s[14:15]
	global_load_dword v83, v5, s[14:15] offset:32
	global_load_dword v84, v5, s[14:15] offset:64
	global_load_dword v85, v5, s[14:15] offset:96
	global_load_dword v86, v5, s[14:15] offset:128
	global_load_dword v87, v5, s[14:15] offset:160
	global_load_dword v88, v5, s[14:15] offset:192
	global_load_dword v89, v5, s[14:15] offset:224
	s_mov_b32 s73, s16
	s_waitcnt vmcnt(16)
	s_cmp_eq_u32 s69, 0
	s_cbranch_scc1 .Lxp_pa0_g
	v_mov_b32_e32 v40, 1.0
	v_mov_b32_e32 v41, 1.0
	v_mov_b32_e32 v42, 1.0
	v_mov_b32_e32 v43, 1.0
	v_mov_b32_e32 v44, 1.0
	v_mov_b32_e32 v45, 1.0
	v_mov_b32_e32 v46, 1.0
	v_mov_b32_e32 v47, 1.0
.Lxp_pa0_g:
	v_mul_f32_e32 v8, v8, v40
	v_mul_f32_e32 v9, v9, v40
	v_mul_f32_e32 v10, v10, v40
	v_mul_f32_e32 v11, v11, v40
	ds_write_b32 v3, v8
	ds_write_b32 v3, v9 offset:4
	ds_write_b32 v3, v10 offset:8
	ds_write_b32 v3, v11 offset:12
	v_mul_f32_e32 v12, v12, v41
	v_mul_f32_e32 v13, v13, v41
	v_mul_f32_e32 v14, v14, v41
	v_mul_f32_e32 v15, v15, v41
	ds_write_b32 v3, v12 offset:1056
	ds_write_b32 v3, v13 offset:1060
	ds_write_b32 v3, v14 offset:1064
	ds_write_b32 v3, v15 offset:1068
	v_mul_f32_e32 v16, v16, v42
	v_mul_f32_e32 v17, v17, v42
	v_mul_f32_e32 v18, v18, v42
	v_mul_f32_e32 v19, v19, v42
	ds_write_b32 v3, v16 offset:2112
	ds_write_b32 v3, v17 offset:2116
	ds_write_b32 v3, v18 offset:2120
	ds_write_b32 v3, v19 offset:2124
	s_waitcnt lgkmcnt(0)
	v_mul_f32_e32 v20, v20, v43
	v_mul_f32_e32 v21, v21, v43
	v_mul_f32_e32 v22, v22, v43
	v_mul_f32_e32 v23, v23, v43
	ds_write_b32 v3, v20 offset:3168
	ds_write_b32 v3, v21 offset:3172
	ds_write_b32 v3, v22 offset:3176
	ds_write_b32 v3, v23 offset:3180
	v_mul_f32_e32 v24, v24, v44
	v_mul_f32_e32 v25, v25, v44
	v_mul_f32_e32 v26, v26, v44
	v_mul_f32_e32 v27, v27, v44
	ds_write_b32 v3, v24 offset:4224
	ds_write_b32 v3, v25 offset:4228
	ds_write_b32 v3, v26 offset:4232
	ds_write_b32 v3, v27 offset:4236
	v_mul_f32_e32 v28, v28, v45
	v_mul_f32_e32 v29, v29, v45
	v_mul_f32_e32 v30, v30, v45
	v_mul_f32_e32 v31, v31, v45
	ds_write_b32 v3, v28 offset:5280
	ds_write_b32 v3, v29 offset:5284
	ds_write_b32 v3, v30 offset:5288
	ds_write_b32 v3, v31 offset:5292
	s_waitcnt lgkmcnt(0)
	v_mul_f32_e32 v32, v32, v46
	v_mul_f32_e32 v33, v33, v46
	v_mul_f32_e32 v34, v34, v46
	v_mul_f32_e32 v35, v35, v46
	ds_write_b32 v3, v32 offset:6336
	ds_write_b32 v3, v33 offset:6340
	ds_write_b32 v3, v34 offset:6344
	ds_write_b32 v3, v35 offset:6348
	v_mul_f32_e32 v36, v36, v47
	v_mul_f32_e32 v37, v37, v47
	v_mul_f32_e32 v38, v38, v47
	v_mul_f32_e32 v39, v39, v47
	ds_write_b32 v3, v36 offset:7392
	ds_write_b32 v3, v37 offset:7396
	ds_write_b32 v3, v38 offset:7400
	ds_write_b32 v3, v39 offset:7404
	s_waitcnt lgkmcnt(0)
	s_mov_b64 s[0:1], s[66:67]
	ds_read_b32 v8, v4
	ds_read_b32 v9, v4 offset:132
	ds_read_b32 v10, v4 offset:264
	ds_read_b32 v11, v4 offset:396
	ds_read_b32 v12, v4 offset:528
	ds_read_b32 v13, v4 offset:660
	ds_read_b32 v14, v4 offset:792
	ds_read_b32 v15, v4 offset:924
	ds_read_b32 v16, v4 offset:32
	ds_read_b32 v17, v4 offset:164
	ds_read_b32 v18, v4 offset:296
	ds_read_b32 v19, v4 offset:428
	s_waitcnt lgkmcnt(4)
	v_cvt_pk_bf16_f32 v8, v8, v9
	v_cvt_pk_bf16_f32 v9, v10, v11
	v_cvt_pk_bf16_f32 v10, v12, v13
	v_cvt_pk_bf16_f32 v11, v14, v15
	global_store_dwordx4 v48, v[8:11], s[0:1]
	s_add_u32 s0, s0, s68
	s_addc_u32 s1, s1, 0
	ds_read_b32 v20, v4 offset:560
	ds_read_b32 v21, v4 offset:692
	ds_read_b32 v22, v4 offset:824
	ds_read_b32 v23, v4 offset:956
	ds_read_b32 v24, v4 offset:64
	ds_read_b32 v25, v4 offset:196
	ds_read_b32 v26, v4 offset:328
	ds_read_b32 v27, v4 offset:460
	s_waitcnt lgkmcnt(4)
	v_cvt_pk_bf16_f32 v16, v16, v17
	v_cvt_pk_bf16_f32 v17, v18, v19
	v_cvt_pk_bf16_f32 v18, v20, v21
	v_cvt_pk_bf16_f32 v19, v22, v23
	global_store_dwordx4 v48, v[16:19], s[0:1]
	s_add_u32 s0, s0, s68
	s_addc_u32 s1, s1, 0
	ds_read_b32 v28, v4 offset:592
	ds_read_b32 v29, v4 offset:724
	ds_read_b32 v30, v4 offset:856
	ds_read_b32 v31, v4 offset:988
	ds_read_b32 v32, v4 offset:96
	ds_read_b32 v33, v4 offset:228
	ds_read_b32 v34, v4 offset:360
	ds_read_b32 v35, v4 offset:492
	s_waitcnt lgkmcnt(4)
	v_cvt_pk_bf16_f32 v24, v24, v25
	v_cvt_pk_bf16_f32 v25, v26, v27
	v_cvt_pk_bf16_f32 v26, v28, v29
	v_cvt_pk_bf16_f32 v27, v30, v31
	global_store_dwordx4 v48, v[24:27], s[0:1]
	s_add_u32 s0, s0, s68
	s_addc_u32 s1, s1, 0
	ds_read_b32 v36, v4 offset:624
	ds_read_b32 v37, v4 offset:756
	ds_read_b32 v38, v4 offset:888
	ds_read_b32 v39, v4 offset:1020
	s_waitcnt lgkmcnt(0)
	v_cvt_pk_bf16_f32 v32, v32, v33
	v_cvt_pk_bf16_f32 v33, v34, v35
	v_cvt_pk_bf16_f32 v34, v36, v37
	v_cvt_pk_bf16_f32 v35, v38, v39
	global_store_dwordx4 v48, v[32:35], s[0:1]
.Lxp_top:
	s_add_i32 s33, s33, s34
	s_cmpk_lt_u32 s33, 0x16e0
	s_cbranch_scc0 .Lxp_lastB
	s_sub_i32 s0, s33, 0x350
	s_cmp_lt_u32 s0, 0x90
	s_cbranch_scc0 .Lxp_a_c1
	s_mul_i32 s30, s0, 171
	s_lshr_b32 s30, s30, 12
	s_mul_i32 s1, s30, 24
	s_sub_i32 s31, s0, s1
	s_mov_b64 s[8:9], s[46:47]
	s_movk_i32 s10, 0x300
	s_mov_b64 s[14:15], s[44:45]
	s_mov_b32 s16, 0
	s_mov_b32 s17, 0x900000
	s_movk_i32 s19, 0x180
	s_lshl_b32 s38, s31, 5
	s_branch .Lxp_a_dec

; #define LAS __attribute__((address_space(3)))
; __device__ __forceinline__ unsigned cvt_pk(float lo, float hi) { unsigned r; asm("v_cvt_pk_bf16_f32 %0, %1, %2" : "=v"(r) : "v"(lo), "v"(hi)); return r; }
; __device__ __forceinline__ void transpose_item(const float* W, int N, const float* gain, bf16_t* WT, int ldt, int dst_row0, int k0, int n0, LAS float* scr, int lane) {
;     { const int kq = lane >> 3, nq = lane & 7;
;       f32x4 v[8]; float gv[8];
; #pragma unroll
;       for (int i = 0; i < 8; ++i) { const int kk = 8 * i + kq; gv[i] = gain ? gain[k0 + kk] : 1.0f; v[i] = *(const f32x4*)(W + (size_t)(k0 + kk) * N + n0 + 4 * nq); }
; #pragma unroll
;       for (int i = 0; i < 8; ++i) { const int kk = 8 * i + kq; LAS float* d = scr + kk * 33 + 4 * nq; d[0] = v[i][0] * gv[i]; d[1] = v[i][1] * gv[i]; d[2] = v[i][2] * gv[i]; d[3] = v[i][3] * gv[i]; } }
;     asm volatile("s_waitcnt lgkmcnt(0)" ::: "memory");
;     const int c = lane & 7;
; #pragma unroll
;     for (int j = 0; j < 4; ++j) { const int n = (lane >> 3) + 8 * j; const LAS float* s = scr + (8 * c) * 33 + n;
;         u32x4 o; o.x = cvt_pk(s[0 * 33], s[1 * 33]); o.y = cvt_pk(s[2 * 33], s[3 * 33]); o.z = cvt_pk(s[4 * 33], s[5 * 33]); o.w = cvt_pk(s[6 * 33], s[7 * 33]);
;         *(u32x4*)(WT + (size_t)(dst_row0 + n) * ldt + k0 + 8 * c) = o; }
;     asm volatile("s_waitcnt lgkmcnt(0)" ::: "memory");
; }
.Lxp_a_dec:
	s_lshl_b32 s30, s30, 6
	s_lshl_b32 s39, s31, 5
	s_mul_i32 s0, s30, s10
	s_add_i32 s0, s0, s39
	s_lshl_b32 s0, s0, 2
	s_add_u32 s8, s8, s0
	s_addc_u32 s9, s9, 0
	s_lshl_b32 s0, s30, 2
	s_add_u32 s14, s14, s0
	s_addc_u32 s15, s15, 0
	s_mul_i32 s0, s38, s19
	s_add_i32 s0, s0, s30
	s_lshl_b32 s0, s0, 1
	s_add_u32 s0, s0, s17
	s_add_u32 s66, s22, s0
	s_addc_u32 s67, s23, 0
	s_lshl_b32 s68, s19, 4
	s_lshl_b32 s0, s19, 1
	v_mad_u32_u24 v48, v1, s0, v6
	s_lshl_b32 s0, s10, 2
	v_mad_u32_u24 v7, v1, s0, v6
	s_lshl_b32 s0, s0, 3
	global_load_dwordx4 v[8:11], v7, s[8:9]
	s_add_u32 s8, s8, s0
	s_addc_u32 s9, s9, 0
	global_load_dwordx4 v[12:15], v7, s[8:9]
	s_add_u32 s8, s8, s0
	s_addc_u32 s9, s9, 0
	global_load_dwordx4 v[16:19], v7, s[8:9]
	s_add_u32 s8, s8, s0
	s_addc_u32 s9, s9, 0
	global_load_dwordx4 v[20:23], v7, s[8:9]
	s_add_u32 s8, s8, s0
	s_addc_u32 s9, s9, 0
	global_load_dwordx4 v[24:27], v7, s[8:9]
	s_add_u32 s8, s8, s0
	s_addc_u32 s9, s9, 0
	global_load_dwordx4 v[28:31], v7, s[8:9]
	s_add_u32 s8, s8, s0
	s_addc_u32 s9, s9, 0
	global_load_dwordx4 v[32:35], v7, s[8:9]
	s_add_u32 s8, s8, s0
	s_addc_u32 s9, s9, 0
	global_load_dwordx4 v[36:39], v7, s[8:9]
	global_load_dword v40, v5, s[14:15]
	global_load_dword v41, v5, s[14:15] offset:32
	global_load_dword v42, v5, s[14:15] offset:64
	global_load_dword v43, v5, s[14:15] offset:96
	global_load_dword v44, v5, s[14:15] offset:128
	global_load_dword v45, v5, s[14:15] offset:160
	global_load_dword v46, v5, s[14:15] offset:192
	global_load_dword v47, v5, s[14:15] offset:224
	s_mov_b32 s69, s16
	s_waitcnt vmcnt(20)
	s_cmp_eq_u32 s73, 0
	s_cbranch_scc1 .Lxp_pb_g
	v_mov_b32_e32 v82, 1.0
	v_mov_b32_e32 v83, 1.0
	v_mov_b32_e32 v84, 1.0
	v_mov_b32_e32 v85, 1.0
	v_mov_b32_e32 v86, 1.0
	v_mov_b32_e32 v87, 1.0
	v_mov_b32_e32 v88, 1.0
	v_mov_b32_e32 v89, 1.0
.Lxp_pb_g:
	v_mul_f32_e32 v50, v50, v82
	v_mul_f32_e32 v51, v51, v82
	v_mul_f32_e32 v52, v52, v82
	v_mul_f32_e32 v53, v53, v82
	ds_write_b32 v3, v50
	ds_write_b32 v3, v51 offset:4
	ds_write_b32 v3, v52 offset:8
	ds_write_b32 v3, v53 offset:12
	v_mul_f32_e32 v54, v54, v83
	v_mul_f32_e32 v55, v55, v83
	v_mul_f32_e32 v56, v56, v83
	v_mul_f32_e32 v57, v57, v83
	ds_write_b32 v3, v54 offset:1056
	ds_write_b32 v3, v55 offset:1060
	ds_write_b32 v3, v56 offset:1064
	ds_write_b32 v3, v57 offset:1068
	v_mul_f32_e32 v58, v58, v84
	v_mul_f32_e32 v59, v59, v84
	v_mul_f32_e32 v60, v60, v84
	v_mul_f32_e32 v61, v61, v84
	ds_write_b32 v3, v58 offset:2112
	ds_write_b32 v3, v59 offset:2116
	ds_write_b32 v3, v60 offset:2120
	ds_write_b32 v3, v61 offset:2124
	s_waitcnt lgkmcnt(0)
	v_mul_f32_e32 v62, v62, v85
	v_mul_f32_e32 v63, v63, v85
	v_mul_f32_e32 v64, v64, v85
	v_mul_f32_e32 v65, v65, v85
	ds_write_b32 v3, v62 offset:3168
	ds_write_b32 v3, v63 offset:3172
	ds_write_b32 v3, v64 offset:3176
	ds_write_b32 v3, v65 offset:3180
	v_mul_f32_e32 v66, v66, v86
	v_mul_f32_e32 v67, v67, v86
	v_mul_f32_e32 v68, v68, v86
	v_mul_f32_e32 v69, v69, v86
	ds_write_b32 v3, v66 offset:4224
	ds_write_b32 v3, v67 offset:4228
	ds_write_b32 v3, v68 offset:4232
	ds_write_b32 v3, v69 offset:4236
	v_mul_f32_e32 v70, v70, v87
	v_mul_f32_e32 v71, v71, v87
	v_mul_f32_e32 v72, v72, v87
	v_mul_f32_e32 v73, v73, v87
	ds_write_b32 v3, v70 offset:5280
	ds_write_b32 v3, v71 offset:5284
	ds_write_b32 v3, v72 offset:5288
	ds_write_b32 v3, v73 offset:5292
	s_waitcnt lgkmcnt(0)
	v_mul_f32_e32 v74, v74, v88
	v_mul_f32_e32 v75, v75, v88
	v_mul_f32_e32 v76, v76, v88
	v_mul_f32_e32 v77, v77, v88
	ds_write_b32 v3, v74 offset:6336
	ds_write_b32 v3, v75 offset:6340
	ds_write_b32 v3, v76 offset:6344
	ds_write_b32 v3, v77 offset:6348
	v_mul_f32_e32 v78, v78, v89
	v_mul_f32_e32 v79, v79, v89
	v_mul_f32_e32 v80, v80, v89
	v_mul_f32_e32 v81, v81, v89
	ds_write_b32 v3, v78 offset:7392
	ds_write_b32 v3, v79 offset:7396
	ds_write_b32 v3, v80 offset:7400
	ds_write_b32 v3, v81 offset:7404
	s_waitcnt lgkmcnt(0)
	s_mov_b64 s[0:1], s[70:71]
	ds_read_b32 v50, v4
	ds_read_b32 v51, v4 offset:132
	ds_read_b32 v52, v4 offset:264
	ds_read_b32 v53, v4 offset:396
	ds_read_b32 v54, v4 offset:528
	ds_read_b32 v55, v4 offset:660
	ds_read_b32 v56, v4 offset:792
	ds_read_b32 v57, v4 offset:924
	ds_read_b32 v58, v4 offset:32
	ds_read_b32 v59, v4 offset:164
	ds_read_b32 v60, v4 offset:296
	ds_read_b32 v61, v4 offset:428
	s_waitcnt lgkmcnt(4)
	v_cvt_pk_bf16_f32 v50, v50, v51
	v_cvt_pk_bf16_f32 v51, v52, v53
	v_cvt_pk_bf16_f32 v52, v54, v55
	v_cvt_pk_bf16_f32 v53, v56, v57
	global_store_dwordx4 v90, v[50:53], s[0:1]
	s_add_u32 s0, s0, s72
	s_addc_u32 s1, s1, 0
	ds_read_b32 v62, v4 offset:560
	ds_read_b32 v63, v4 offset:692
	ds_read_b32 v64, v4 offset:824
	ds_read_b32 v65, v4 offset:956
	ds_read_b32 v66, v4 offset:64
	ds_read_b32 v67, v4 offset:196
	ds_read_b32 v68, v4 offset:328
	ds_read_b32 v69, v4 offset:460
	s_waitcnt lgkmcnt(4)
	v_cvt_pk_bf16_f32 v58, v58, v59
	v_cvt_pk_bf16_f32 v59, v60, v61
	v_cvt_pk_bf16_f32 v60, v62, v63
	v_cvt_pk_bf16_f32 v61, v64, v65
	global_store_dwordx4 v90, v[58:61], s[0:1]
	s_add_u32 s0, s0, s72
	s_addc_u32 s1, s1, 0
	ds_read_b32 v70, v4 offset:592
	ds_read_b32 v71, v4 offset:724
	ds_read_b32 v72, v4 offset:856
	ds_read_b32 v73, v4 offset:988
	ds_read_b32 v74, v4 offset:96
	ds_read_b32 v75, v4 offset:228
	ds_read_b32 v76, v4 offset:360
	ds_read_b32 v77, v4 offset:492
	s_waitcnt lgkmcnt(4)
	v_cvt_pk_bf16_f32 v66, v66, v67
	v_cvt_pk_bf16_f32 v67, v68, v69
	v_cvt_pk_bf16_f32 v68, v70, v71
	v_cvt_pk_bf16_f32 v69, v72, v73
	global_store_dwordx4 v90, v[66:69], s[0:1]
	s_add_u32 s0, s0, s72
	s_addc_u32 s1, s1, 0
	ds_read_b32 v78, v4 offset:624
	ds_read_b32 v79, v4 offset:756
	ds_read_b32 v80, v4 offset:888
	ds_read_b32 v81, v4 offset:1020
	s_waitcnt lgkmcnt(0)
	v_cvt_pk_bf16_f32 v74, v74, v75
	v_cvt_pk_bf16_f32 v75, v76, v77
	v_cvt_pk_bf16_f32 v76, v78, v79
	v_cvt_pk_bf16_f32 v77, v80, v81
	global_store_dwordx4 v90, v[74:77], s[0:1]
	s_add_i32 s33, s33, s34
	s_cmpk_lt_u32 s33, 0x16e0
	s_cbranch_scc0 .Lxp_lastA
	s_sub_i32 s0, s33, 0x350
	s_cmp_lt_u32 s0, 0x90
	s_cbranch_scc0 .Lxp_b_c1
	s_mul_i32 s30, s0, 171
	s_lshr_b32 s30, s30, 12
	s_mul_i32 s1, s30, 24
	s_sub_i32 s31, s0, s1
	s_mov_b64 s[8:9], s[46:47]
	s_movk_i32 s10, 0x300
	s_mov_b64 s[14:15], s[44:45]
	s_mov_b32 s16, 0
	s_mov_b32 s17, 0x900000
	s_movk_i32 s19, 0x180
	s_lshl_b32 s38, s31, 5
	s_branch .Lxp_b_dec

; #define LAS __attribute__((address_space(3)))
; __device__ __forceinline__ unsigned cvt_pk(float lo, float hi) { unsigned r; asm("v_cvt_pk_bf16_f32 %0, %1, %2" : "=v"(r) : "v"(lo), "v"(hi)); return r; }
; __device__ __forceinline__ void transpose_item(const float* W, int N, const float* gain, bf16_t* WT, int ldt, int dst_row0, int k0, int n0, LAS float* scr, int lane) {
;     { const int kq = lane >> 3, nq = lane & 7;
;       f32x4 v[8]; float gv[8];
; #pragma unroll
;       for (int i = 0; i < 8; ++i) { const int kk = 8 * i + kq; gv[i] = gain ? gain[k0 + kk] : 1.0f; v[i] = *(const f32x4*)(W + (size_t)(k0 + kk) * N + n0 + 4 * nq); }
; #pragma unroll
;       for (int i = 0; i < 8; ++i) { const int kk = 8 * i + kq; LAS float* d = scr + kk * 33 + 4 * nq; d[0] = v[i][0] * gv[i]; d[1] = v[i][1] * gv[i]; d[2] = v[i][2] * gv[i]; d[3] = v[i][3] * gv[i]; } }
;     asm volatile("s_waitcnt lgkmcnt(0)" ::: "memory");
;     const int c = lane & 7;
; #pragma unroll
;     for (int j = 0; j < 4; ++j) { const int n = (lane >> 3) + 8 * j; const LAS float* s = scr + (8 * c) * 33 + n;
;         u32x4 o; o.x = cvt_pk(s[0 * 33], s[1 * 33]); o.y = cvt_pk(s[2 * 33], s[3 * 33]); o.z = cvt_pk(s[4 * 33], s[5 * 33]); o.w = cvt_pk(s[6 * 33], s[7 * 33]);
;         *(u32x4*)(WT + (size_t)(dst_row0 + n) * ldt + k0 + 8 * c) = o; }
;     asm volatile("s_waitcnt lgkmcnt(0)" ::: "memory");
; }
.Lxp_b_dec:
	s_lshl_b32 s30, s30, 6
	s_lshl_b32 s39, s31, 5
	s_mul_i32 s0, s30, s10
	s_add_i32 s0, s0, s39
	s_lshl_b32 s0, s0, 2
	s_add_u32 s8, s8, s0
	s_addc_u32 s9, s9, 0
	s_lshl_b32 s0, s30, 2
	s_add_u32 s14, s14, s0
	s_addc_u32 s15, s15, 0
	s_mul_i32 s0, s38, s19
	s_add_i32 s0, s0, s30
	s_lshl_b32 s0, s0, 1
	s_add_u32 s0, s0, s17
	s_add_u32 s70, s22, s0
	s_addc_u32 s71, s23, 0
	s_lshl_b32 s72, s19, 4
	s_lshl_b32 s0, s19, 1
	v_mad_u32_u24 v90, v1, s0, v6
	s_lshl_b32 s0, s10, 2
	v_mad_u32_u24 v7, v1, s0, v6
	s_lshl_b32 s0, s0, 3
	global_load_dwordx4 v[50:53], v7, s[8:9]
	s_add_u32 s8, s8, s0
	s_addc_u32 s9, s9, 0
	global_load_dwordx4 v[54:57], v7, s[8:9]
	s_add_u32 s8, s8, s0
	s_addc_u32 s9, s9, 0
	global_load_dwordx4 v[58:61], v7, s[8:9]
	s_add_u32 s8, s8, s0
	s_addc_u32 s9, s9, 0
	global_load_dwordx4 v[62:65], v7, s[8:9]
	s_add_u32 s8, s8, s0
	s_addc_u32 s9, s9, 0
	global_load_dwordx4 v[66:69], v7, s[8:9]
	s_add_u32 s8, s8, s0
	s_addc_u32 s9, s9, 0
	global_load_dwordx4 v[70:73], v7, s[8:9]
	s_add_u32 s8, s8, s0
	s_addc_u32 s9, s9, 0
	global_load_dwordx4 v[74:77], v7, s[8:9]
	s_add_u32 s8, s8, s0
	s_addc_u32 s9, s9, 0
	global_load_dwordx4 v[78:81], v7, s[8:9]
	global_load_dword v82, v5, s[14:15]
	global_load_dword v83, v5, s[14:15] offset:32
	global_load_dword v84, v5, s[14:15] offset:64
	global_load_dword v85, v5, s[14:15] offset:96
	global_load_dword v86, v5, s[14:15] offset:128
	global_load_dword v87, v5, s[14:15] offset:160
	global_load_dword v88, v5, s[14:15] offset:192
	global_load_dword v89, v5, s[14:15] offset:224
	s_mov_b32 s73, s16
	s_waitcnt vmcnt(20)
	s_cmp_eq_u32 s69, 0
	s_cbranch_scc1 .Lxp_pa_g
	v_mov_b32_e32 v40, 1.0
	v_mov_b32_e32 v41, 1.0
	v_mov_b32_e32 v42, 1.0
	v_mov_b32_e32 v43, 1.0
	v_mov_b32_e32 v44, 1.0
	v_mov_b32_e32 v45, 1.0
	v_mov_b32_e32 v46, 1.0
	v_mov_b32_e32 v47, 1.0
.Lxp_pa_g:
	v_mul_f32_e32 v8, v8, v40
	v_mul_f32_e32 v9, v9, v40
	v_mul_f32_e32 v10, v10, v40
	v_mul_f32_e32 v11, v11, v40
	ds_write_b32 v3, v8
	ds_write_b32 v3, v9 offset:4
	ds_write_b32 v3, v10 offset:8
	ds_write_b32 v3, v11 offset:12
	v_mul_f32_e32 v12, v12, v41
	v_mul_f32_e32 v13, v13, v41
	v_mul_f32_e32 v14, v14, v41
	v_mul_f32_e32 v15, v15, v41
	ds_write_b32 v3, v12 offset:1056
	ds_write_b32 v3, v13 offset:1060
	ds_write_b32 v3, v14 offset:1064
	ds_write_b32 v3, v15 offset:1068
	v_mul_f32_e32 v16, v16, v42
	v_mul_f32_e32 v17, v17, v42
	v_mul_f32_e32 v18, v18, v42
	v_mul_f32_e32 v19, v19, v42
	ds_write_b32 v3, v16 offset:2112
	ds_write_b32 v3, v17 offset:2116
	ds_write_b32 v3, v18 offset:2120
	ds_write_b32 v3, v19 offset:2124
	s_waitcnt lgkmcnt(0)
	v_mul_f32_e32 v20, v20, v43
	v_mul_f32_e32 v21, v21, v43
	v_mul_f32_e32 v22, v22, v43
	v_mul_f32_e32 v23, v23, v43
	ds_write_b32 v3, v20 offset:3168
	ds_write_b32 v3, v21 offset:3172
	ds_write_b32 v3, v22 offset:3176
	ds_write_b32 v3, v23 offset:3180
	v_mul_f32_e32 v24, v24, v44
	v_mul_f32_e32 v25, v25, v44
	v_mul_f32_e32 v26, v26, v44
	v_mul_f32_e32 v27, v27, v44
	ds_write_b32 v3, v24 offset:4224
	ds_write_b32 v3, v25 offset:4228
	ds_write_b32 v3, v26 offset:4232
	ds_write_b32 v3, v27 offset:4236
	v_mul_f32_e32 v28, v28, v45
	v_mul_f32_e32 v29, v29, v45
	v_mul_f32_e32 v30, v30, v45
	v_mul_f32_e32 v31, v31, v45
	ds_write_b32 v3, v28 offset:5280
	ds_write_b32 v3, v29 offset:5284
	ds_write_b32 v3, v30 offset:5288
	ds_write_b32 v3, v31 offset:5292
	s_waitcnt lgkmcnt(0)
	v_mul_f32_e32 v32, v32, v46
	v_mul_f32_e32 v33, v33, v46
	v_mul_f32_e32 v34, v34, v46
	v_mul_f32_e32 v35, v35, v46
	ds_write_b32 v3, v32 offset:6336
	ds_write_b32 v3, v33 offset:6340
	ds_write_b32 v3, v34 offset:6344
	ds_write_b32 v3, v35 offset:6348
	v_mul_f32_e32 v36, v36, v47
	v_mul_f32_e32 v37, v37, v47
	v_mul_f32_e32 v38, v38, v47
	v_mul_f32_e32 v39, v39, v47
	ds_write_b32 v3, v36 offset:7392
	ds_write_b32 v3, v37 offset:7396
	ds_write_b32 v3, v38 offset:7400
	ds_write_b32 v3, v39 offset:7404
	s_waitcnt lgkmcnt(0)
	s_mov_b64 s[0:1], s[66:67]
	ds_read_b32 v8, v4
	ds_read_b32 v9, v4 offset:132
	ds_read_b32 v10, v4 offset:264
	ds_read_b32 v11, v4 offset:396
	ds_read_b32 v12, v4 offset:528
	ds_read_b32 v13, v4 offset:660
	ds_read_b32 v14, v4 offset:792
	ds_read_b32 v15, v4 offset:924
	ds_read_b32 v16, v4 offset:32
	ds_read_b32 v17, v4 offset:164
	ds_read_b32 v18, v4 offset:296
	ds_read_b32 v19, v4 offset:428
	s_waitcnt lgkmcnt(4)
	v_cvt_pk_bf16_f32 v8, v8, v9
	v_cvt_pk_bf16_f32 v9, v10, v11
	v_cvt_pk_bf16_f32 v10, v12, v13
	v_cvt_pk_bf16_f32 v11, v14, v15
	global_store_dwordx4 v48, v[8:11], s[0:1]
	s_add_u32 s0, s0, s68
	s_addc_u32 s1, s1, 0
	ds_read_b32 v20, v4 offset:560
	ds_read_b32 v21, v4 offset:692
	ds_read_b32 v22, v4 offset:824
	ds_read_b32 v23, v4 offset:956
	ds_read_b32 v24, v4 offset:64
	ds_read_b32 v25, v4 offset:196
	ds_read_b32 v26, v4 offset:328
	ds_read_b32 v27, v4 offset:460
	s_waitcnt lgkmcnt(4)
	v_cvt_pk_bf16_f32 v16, v16, v17
	v_cvt_pk_bf16_f32 v17, v18, v19
	v_cvt_pk_bf16_f32 v18, v20, v21
	v_cvt_pk_bf16_f32 v19, v22, v23
	global_store_dwordx4 v48, v[16:19], s[0:1]
	s_add_u32 s0, s0, s68
	s_addc_u32 s1, s1, 0
	ds_read_b32 v28, v4 offset:592
	ds_read_b32 v29, v4 offset:724
	ds_read_b32 v30, v4 offset:856
	ds_read_b32 v31, v4 offset:988
	ds_read_b32 v32, v4 offset:96
	ds_read_b32 v33, v4 offset:228
	ds_read_b32 v34, v4 offset:360
	ds_read_b32 v35, v4 offset:492
	s_waitcnt lgkmcnt(4)
	v_cvt_pk_bf16_f32 v24, v24, v25
	v_cvt_pk_bf16_f32 v25, v26, v27
	v_cvt_pk_bf16_f32 v26, v28, v29
	v_cvt_pk_bf16_f32 v27, v30, v31
	global_store_dwordx4 v48, v[24:27], s[0:1]
	s_add_u32 s0, s0, s68
	s_addc_u32 s1, s1, 0
	ds_read_b32 v36, v4 offset:624
	ds_read_b32 v37, v4 offset:756
	ds_read_b32 v38, v4 offset:888
	ds_read_b32 v39, v4 offset:1020
	s_waitcnt lgkmcnt(0)
	v_cvt_pk_bf16_f32 v32, v32, v33
	v_cvt_pk_bf16_f32 v33, v34, v35
	v_cvt_pk_bf16_f32 v34, v36, v37
	v_cvt_pk_bf16_f32 v35, v38, v39
	global_store_dwordx4 v48, v[32:35], s[0:1]
	s_branch .Lxp_top
.Lxp_lastA:
	s_waitcnt vmcnt(0)
	s_cmp_eq_u32 s69, 0
	s_cbranch_scc1 .Lxp_la_g
	v_mov_b32_e32 v40, 1.0
	v_mov_b32_e32 v41, 1.0
	v_mov_b32_e32 v42, 1.0
	v_mov_b32_e32 v43, 1.0
	v_mov_b32_e32 v44, 1.0
	v_mov_b32_e32 v45, 1.0
	v_mov_b32_e32 v46, 1.0
	v_mov_b32_e32 v47, 1.0

; #define LAS __attribute__((address_space(3)))
; __device__ __forceinline__ unsigned cvt_pk(float lo, float hi) { unsigned r; asm("v_cvt_pk_bf16_f32 %0, %1, %2" : "=v"(r) : "v"(lo), "v"(hi)); return r; }
; __device__ __forceinline__ void transpose_item(const float* W, int N, const float* gain, bf16_t* WT, int ldt, int dst_row0, int k0, int n0, LAS float* scr, int lane) {
;     { const int kq = lane >> 3, nq = lane & 7;
;       f32x4 v[8]; float gv[8];
; #pragma unroll
;       for (int i = 0; i < 8; ++i) { const int kk = 8 * i + kq; gv[i] = gain ? gain[k0 + kk] : 1.0f; v[i] = *(const f32x4*)(W + (size_t)(k0 + kk) * N + n0 + 4 * nq); }
; #pragma unroll
;       for (int i = 0; i < 8; ++i) { const int kk = 8 * i + kq; LAS float* d = scr + kk * 33 + 4 * nq; d[0] = v[i][0] * gv[i]; d[1] = v[i][1] * gv[i]; d[2] = v[i][2] * gv[i]; d[3] = v[i][3] * gv[i]; } }
;     asm volatile("s_waitcnt lgkmcnt(0)" ::: "memory");
;     const int c = lane & 7;
; #pragma unroll
;     for (int j = 0; j < 4; ++j) { const int n = (lane >> 3) + 8 * j; const LAS float* s = scr + (8 * c) * 33 + n;
;         u32x4 o; o.x = cvt_pk(s[0 * 33], s[1 * 33]); o.y = cvt_pk(s[2 * 33], s[3 * 33]); o.z = cvt_pk(s[4 * 33], s[5 * 33]); o.w = cvt_pk(s[6 * 33], s[7 * 33]);
;         *(u32x4*)(WT + (size_t)(dst_row0 + n) * ldt + k0 + 8 * c) = o; }
;     asm volatile("s_waitcnt lgkmcnt(0)" ::: "memory");
; }
.Lxp_lastB:
	s_waitcnt vmcnt(0)
	s_cmp_eq_u32 s73, 0
	s_cbranch_scc1 .Lxp_lb_g
	v_mov_b32_e32 v82, 1.0
	v_mov_b32_e32 v83, 1.0
	v_mov_b32_e32 v84, 1.0
	v_mov_b32_e32 v85, 1.0
	v_mov_b32_e32 v86, 1.0
	v_mov_b32_e32 v87, 1.0
	v_mov_b32_e32 v88, 1.0
	v_mov_b32_e32 v89, 1.0
.Lxp_lb_g:
	v_mul_f32_e32 v50, v50, v82
	v_mul_f32_e32 v51, v51, v82
	v_mul_f32_e32 v52, v52, v82
	v_mul_f32_e32 v53, v53, v82
	ds_write_b32 v3, v50
	ds_write_b32 v3, v51 offset:4
	ds_write_b32 v3, v52 offset:8
	ds_write_b32 v3, v53 offset:12
	v_mul_f32_e32 v54, v54, v83
	v_mul_f32_e32 v55, v55, v83
	v_mul_f32_e32 v56, v56, v83
	v_mul_f32_e32 v57, v57, v83
	ds_write_b32 v3, v54 offset:1056
	ds_write_b32 v3, v55 offset:1060
	ds_write_b32 v3, v56 offset:1064
	ds_write_b32 v3, v57 offset:1068
	v_mul_f32_e32 v58, v58, v84
	v_mul_f32_e32 v59, v59, v84
	v_mul_f32_e32 v60, v60, v84
	v_mul_f32_e32 v61, v61, v84
	ds_write_b32 v3, v58 offset:2112
	ds_write_b32 v3, v59 offset:2116
	ds_write_b32 v3, v60 offset:2120
	ds_write_b32 v3, v61 offset:2124
	s_waitcnt lgkmcnt(0)
	v_mul_f32_e32 v62, v62, v85
	v_mul_f32_e32 v63, v63, v85
	v_mul_f32_e32 v64, v64, v85
	v_mul_f32_e32 v65, v65, v85
	ds_write_b32 v3, v62 offset:3168
	ds_write_b32 v3, v63 offset:3172
	ds_write_b32 v3, v64 offset:3176
	ds_write_b32 v3, v65 offset:3180
	v_mul_f32_e32 v66, v66, v86
	v_mul_f32_e32 v67, v67, v86
	v_mul_f32_e32 v68, v68, v86
	v_mul_f32_e32 v69, v69, v86
	ds_write_b32 v3, v66 offset:4224
	ds_write_b32 v3, v67 offset:4228
	ds_write_b32 v3, v68 offset:4232
	ds_write_b32 v3, v69 offset:4236
	v_mul_f32_e32 v70, v70, v87
	v_mul_f32_e32 v71, v71, v87
	v_mul_f32_e32 v72, v72, v87
	v_mul_f32_e32 v73, v73, v87
	ds_write_b32 v3, v70 offset:5280
	ds_write_b32 v3, v71 offset:5284
	ds_write_b32 v3, v72 offset:5288
	ds_write_b32 v3, v73 offset:5292
	s_waitcnt lgkmcnt(0)
	v_mul_f32_e32 v74, v74, v88
	v_mul_f32_e32 v75, v75, v88
	v_mul_f32_e32 v76, v76, v88
	v_mul_f32_e32 v77, v77, v88
	ds_write_b32 v3, v74 offset:6336
	ds_write_b32 v3, v75 offset:6340
	ds_write_b32 v3, v76 offset:6344
	ds_write_b32 v3, v77 offset:6348
	v_mul_f32_e32 v78, v78, v89
	v_mul_f32_e32 v79, v79, v89
	v_mul_f32_e32 v80, v80, v89
	v_mul_f32_e32 v81, v81, v89
	ds_write_b32 v3, v78 offset:7392
	ds_write_b32 v3, v79 offset:7396
	ds_write_b32 v3, v80 offset:7400
	ds_write_b32 v3, v81 offset:7404
	s_waitcnt lgkmcnt(0)
	s_mov_b64 s[0:1], s[70:71]
	ds_read_b32 v50, v4
	ds_read_b32 v51, v4 offset:132
	ds_read_b32 v52, v4 offset:264
	ds_read_b32 v53, v4 offset:396
	ds_read_b32 v54, v4 offset:528
	ds_read_b32 v55, v4 offset:660
	ds_read_b32 v56, v4 offset:792
	ds_read_b32 v57, v4 offset:924
	ds_read_b32 v58, v4 offset:32
	ds_read_b32 v59, v4 offset:164
	ds_read_b32 v60, v4 offset:296
	ds_read_b32 v61, v4 offset:428
	s_waitcnt lgkmcnt(4)
	v_cvt_pk_bf16_f32 v50, v50, v51
	v_cvt_pk_bf16_f32 v51, v52, v53
	v_cvt_pk_bf16_f32 v52, v54, v55
	v_cvt_pk_bf16_f32 v53, v56, v57
	global_store_dwordx4 v90, v[50:53], s[0:1]
	s_add_u32 s0, s0, s72
	s_addc_u32 s1, s1, 0
	ds_read_b32 v62, v4 offset:560
	ds_read_b32 v63, v4 offset:692
	ds_read_b32 v64, v4 offset:824
	ds_read_b32 v65, v4 offset:956
	ds_read_b32 v66, v4 offset:64
	ds_read_b32 v67, v4 offset:196
	ds_read_b32 v68, v4 offset:328
	ds_read_b32 v69, v4 offset:460
	s_waitcnt lgkmcnt(4)
	v_cvt_pk_bf16_f32 v58, v58, v59
	v_cvt_pk_bf16_f32 v59, v60, v61
	v_cvt_pk_bf16_f32 v60, v62, v63
	v_cvt_pk_bf16_f32 v61, v64, v65
	global_store_dwordx4 v90, v[58:61], s[0:1]
	s_add_u32 s0, s0, s72
	s_addc_u32 s1, s1, 0
	ds_read_b32 v70, v4 offset:592
	ds_read_b32 v71, v4 offset:724
	ds_read_b32 v72, v4 offset:856
	ds_read_b32 v73, v4 offset:988
	ds_read_b32 v74, v4 offset:96
	ds_read_b32 v75, v4 offset:228
	ds_read_b32 v76, v4 offset:360
	ds_read_b32 v77, v4 offset:492
	s_waitcnt lgkmcnt(4)
	v_cvt_pk_bf16_f32 v66, v66, v67
	v_cvt_pk_bf16_f32 v67, v68, v69
	v_cvt_pk_bf16_f32 v68, v70, v71
	v_cvt_pk_bf16_f32 v69, v72, v73
	global_store_dwordx4 v90, v[66:69], s[0:1]
	s_add_u32 s0, s0, s72
	s_addc_u32 s1, s1, 0
	ds_read_b32 v78, v4 offset:624
	ds_read_b32 v79, v4 offset:756
	ds_read_b32 v80, v4 offset:888
	ds_read_b32 v81, v4 offset:1020
	s_waitcnt lgkmcnt(0)
	v_cvt_pk_bf16_f32 v74, v74, v75
	v_cvt_pk_bf16_f32 v75, v76, v77
	v_cvt_pk_bf16_f32 v76, v78, v79
	v_cvt_pk_bf16_f32 v77, v80, v81
	global_store_dwordx4 v90, v[74:77], s[0:1]
.Lxp_done:
.LBB0_317:
	s_or_b64 exec, exec, s[4:5]
